# strategy 4: static s_setprio 1 for waves 0-3 (Vn producers) in the gated-delta scan task, reset at task exit
# speedup vs baseline: 1.0009x; 1.0009x over previous
; #define TIDX opaque_tid()
; #define WSP(T, off) ((T*)(__attribute__((address_space(1))) T*)(launder_ws(AWS, (off))))
; template <int TYPE>
; __device__ __forceinline__ void scan_load(ScanRegs& R, const Args& a, size_t ci, int w, int mt, int fr, int fq, int e0) {
;     if (TYPE == 0) {
;         {
;             const float* U = WSP(const float, WS_GU) + (ci * 64 + mt * 16 + 4 * fq) * 128 + e0 + fr;
;             R.u = (f32x4){U[0], U[128], U[256], U[384]};
;             const bf16_t* Wn = WSP(const bf16_t, (w < 4) ? WS_GWN : WS_GQD) + (ci * 64 + mt * 16 + fr) * 128 + fq * 8;
;             R.a10 = *(const bf16x8*)(Wn); R.a11 = *(const bf16x8*)(Wn + 32); R.a12 = *(const bf16x8*)(Wn + 64); R.a13 = *(const bf16x8*)(Wn + 96);
;             const bf16_t* At = WSP(const bf16_t, WS_GAT) + (ci * 64 + mt * 16 + fr) * 64 + fq * 8;
;             R.at0 = *(const bf16x8*)(At); R.at1 = *(const bf16x8*)(At + 32);
;         }
;         const float last = WSP(const float, WS_GLAST)[ci];
;         R.dl = (f32x4){last, last, last, last};
;         const bf16_t* Kt = WSP(const bf16_t, WS_GKT) + (ci * 128 + 16 * w + fr) * 64 + fq * 8;
;         R.kt0 = *(const bf16x8*)(Kt); R.kt1 = *(const bf16x8*)(Kt + 32);
; template <int TYPE>
; __device__ __forceinline__ void scan_task(const Args& a, int task, unsigned char* lds) {
;     const int bh = task >> 3, es = task & 7, e0 = es * 16, b = bh / 5, h = bh % 5;
;     const int tid = TIDX, w = __builtin_amdgcn_readfirstlane(tid >> 6), lane = tid & 63, fr = lane & 15, fq = lane >> 4;
;     bf16_t* St = (bf16_t*)lds;
;     bf16_t* Vn = St + 16 * 136;
;     __syncthreads();
;     for (int i = tid; i < 16 * 136; i += 512) St[i] = 0;
;     f32x4 Sacc = zero4();
;     const int mt = w & 3;
;     float* Obase = WSP(float, TYPE == 0 ? WS_OG : WS_OH) + ((size_t)(b * SEQ + mt * 16 + 4 * fq)) * 640 + h * 128 + e0 + fr;
;     ScanRegs R0, R1;
;     scan_load<TYPE>(R0, a, (size_t)bh * 64, w, mt, fr, fq, e0);
;     __syncthreads();
;     for (int n = 0; n < NCH; n += 2) {
;         scan_load<TYPE>(R1, a, (size_t)bh * 64 + n + 1, w, mt, fr, fq, e0);
.LBB0_563:
	s_or_b64 exec, exec, s[2:3]
	s_add_i32 s45, s13, 0xffffff80
	s_lshl_b32 s3, s45, 4
	s_ashr_i32 s50, s15, 6
	s_cmp_lt_u32 s50, 4
	s_cbranch_scc0 .Lscan_prio_skip
	s_setprio 1
.Lscan_prio_skip:
	s_lshr_b32 s2, s45, 3
	s_and_b32 s14, s3, 0x70
	s_and_b32 s15, s50, 3
	s_cmp_gt_u32 s45, 39
	s_cselect_b32 s21, 0x1000, 0
	s_lshl_b32 s20, s15, 4
	s_lshl_b32 s24, s2, 7
	s_mov_b32 s44, 0
	s_mov_b64 s[22:23], s[0:1]
	s_or_b32 s21, s21, s20
	s_add_i32 s25, s24, 0xfffffd80
	s_cmp_lt_u32 s45, 40
	s_load_dwordx2 s[40:41], s[22:23], 0xd0
	s_mov_b64 s[42:43], 0x27be8a00
	s_mov_b64 s[22:23], s[0:1]
	s_cselect_b32 s92, s24, s25
	s_load_dwordx2 s[24:25], s[22:23], 0xd0
	s_lshl_b32 s22, s2, 6
	s_mov_b64 s[26:27], 0x22198000
	s_mov_b32 s23, s93
	s_waitcnt lgkmcnt(0)
	s_add_u32 s24, s24, s26
	v_bfe_u32 v38, v0, 4, 2
	s_addc_u32 s25, s25, s27
	s_lshl_b64 s[26:27], s[22:23], 6
	v_lshlrev_b32_e32 v98, 2, v38
	s_or_b32 s48, s26, s20
	v_or_b32_e32 v4, s48, v98
	v_mov_b32_e32 v5, s27
	v_and_b32_e32 v96, 15, v0
	v_lshlrev_b64 v[0:1], 9, v[4:5]
	v_lshl_add_u64 v[0:1], s[24:25], 0, v[0:1]
	s_lshl_b32 s24, s14, 2
	s_mov_b32 s25, s93
	v_lshl_add_u64 v[0:1], v[0:1], 0, s[24:25]
	v_lshlrev_b32_e32 v100, 2, v96
	v_mov_b32_e32 v101, v215
	v_lshl_add_u64 v[6:7], v[0:1], 0, v[100:101]
	s_mov_b64 s[24:25], s[0:1]
	global_load_dword v0, v[6:7], off
	global_load_dword v1, v[6:7], off offset:512
	global_load_dword v2, v[6:7], off offset:1024
	global_load_dword v3, v[6:7], off offset:1536
	s_cmp_gt_i32 s50, 3
	s_load_dwordx2 s[38:39], s[24:25], 0xd0
	s_cselect_b64 s[24:25], -1, 0
	s_cmp_lt_i32 s50, 4
	s_cselect_b64 s[26:27], -1, 0
	s_and_b64 s[46:47], s[26:27], exec
	s_mov_b32 s2, 0x23598000
	s_mov_b32 s3, 0
	s_cselect_b32 s2, s2, 0x23f98000
	s_mov_b64 s[46:47], s[2:3]
	s_waitcnt lgkmcnt(0)
	s_add_u32 s38, s38, s46
	v_or_b32_e32 v4, s48, v96
	s_addc_u32 s39, s39, s47
	v_lshlrev_b64 v[6:7], 8, v[4:5]
	v_lshl_add_u64 v[6:7], s[38:39], 0, v[6:7]
	v_lshlrev_b32_e32 v102, 4, v38
	v_mov_b32_e32 v103, v215
	v_lshl_add_u64 v[6:7], v[6:7], 0, v[102:103]
	s_mov_b64 s[38:39], s[0:1]
	global_load_dwordx4 v[20:23], v[6:7], off
	global_load_dwordx4 v[24:27], v[6:7], off offset:64
	global_load_dwordx4 v[28:31], v[6:7], off offset:128
	global_load_dwordx4 v[32:35], v[6:7], off offset:192
	s_load_dwordx2 s[38:39], s[38:39], 0xd0
	s_mov_b64 s[46:47], 0x25398000
	v_lshlrev_b64 v[4:5], 7, v[4:5]
	s_mov_b64 s[48:49], 0x24998000
	s_waitcnt lgkmcnt(0)
	s_add_u32 s38, s38, s46
	s_addc_u32 s39, s39, s47
	v_lshl_add_u64 v[4:5], s[38:39], 0, v[4:5]
	v_lshl_add_u64 v[4:5], v[4:5], 0, v[102:103]
	s_mov_b64 s[38:39], s[0:1]
	global_load_dwordx4 v[8:11], v[4:5], off
	global_load_dwordx4 v[12:15], v[4:5], off offset:64
	s_load_dwordx2 s[38:39], s[38:39], 0xd0
	s_mov_b64 s[46:47], 0x25898000
	v_or_b32_e32 v36, s21, v98
	v_mul_u32_u24_e32 v39, 0x280, v36
	s_waitcnt lgkmcnt(0)
	s_add_u32 s46, s38, s46
	s_addc_u32 s47, s39, s47
	s_lshl_b64 s[38:39], s[22:23], 2
	s_add_u32 s46, s46, s38
	s_addc_u32 s47, s47, s39
	global_load_dword v118, v215, s[46:47]
	s_mov_b64 s[46:47], s[0:1]
	s_load_dwordx2 s[46:47], s[46:47], 0xd0
	v_lshlrev_b32_e32 v40, 7, v96
	v_lshlrev_b32_e32 v214, 2, v39
	v_lshlrev_b32_e32 v104, 3, v38
	s_waitcnt lgkmcnt(0)
	s_add_u32 s46, s46, s48
	s_addc_u32 s47, s47, s49
	s_lshl_b32 s51, s50, 4
	s_lshl_b64 s[48:49], s[22:23], 7
	s_ashr_i32 s52, s51, 31
	s_add_u32 s48, s48, s51
	s_addc_u32 s49, s49, s52
	v_or_b32_e32 v4, s48, v96
	v_mov_b32_e32 v5, s49
	v_lshlrev_b64 v[4:5], 7, v[4:5]
	v_lshl_add_u64 v[4:5], s[46:47], 0, v[4:5]
	v_lshl_add_u64 v[4:5], v[4:5], 0, v[102:103]
	global_load_dwordx4 v[16:19], v[4:5], off
	s_nop 0
	global_load_dwordx4 v[4:7], v[4:5], off offset:64
	s_and_b32 s45, s45, 7
	s_movk_i32 s46, 0x110
	s_lshl_b32 s45, s45, 6
	v_mad_u32_u24 v97, v96, s46, 0
	s_add_u32 s46, s42, s45
	s_addc_u32 s47, s43, 0
	s_lshl_b64 s[42:43], s[92:93], 2
	s_add_u32 s42, s46, s42
	s_addc_u32 s43, s47, s43
	s_add_u32 s40, s40, s42
	s_addc_u32 s41, s41, s43
	s_lshl_b64 s[42:43], s[22:23], 15
	s_lshl_b32 s46, s15, 13
	v_or_b32_e32 v36, s51, v96
	v_mov_b32_e32 v37, s52
	v_sub_u32_e32 v41, v97, v40
	s_or_b32 s42, s42, s46
	v_lshl_add_u32 v99, s15, 5, v41
	v_lshlrev_b64 v[106:107], 7, v[36:37]
	v_lshl_add_u64 v[108:109], s[40:41], 0, v[214:215]
	s_lshl_b64 s[40:41], s[22:23], 14
	v_lshl_or_b32 v36, v38, 11, s42
	v_mov_b32_e32 v113, s43
	s_lshl_b64 s[42:43], s[22:23], 13
	s_lshl_b32 s23, s15, 11
	s_lshl_b32 s15, s15, 12
	v_or_b32_e32 v36, s45, v36
	s_or_b32 s15, s40, s15
	v_lshl_add_u32 v42, s50, 5, v97
	v_or_b32_e32 v112, 0x8400, v36
	s_or_b32 s23, s42, s23
	v_lshl_or_b32 v36, v96, 8, s15
	s_mov_b32 s21, s93
	v_add_u32_e32 v105, v41, v102
	s_or_b32 s38, s38, 4
	v_lshl_add_u64 v[110:111], s[40:41], 0, v[106:107]
	v_or_b32_e32 v114, s23, v40
	v_mov_b32_e32 v115, s43
	v_or_b32_e32 v116, 0x4080, v36
	v_mov_b32_e32 v117, s41
	s_waitcnt vmcnt(14)
	v_mov_b32_e32 v72, s44
	s_lshl_b32 s48, s14, 2
	v_add_u32_e32 v119, v42, v104
	s_mov_b32 s14, s3
	v_mov_b32_e32 v73, s44
	v_mov_b32_e32 v74, s44
	v_mov_b32_e32 v75, s44
	s_barrier
	s_branch .LBB0_565

; template <int TYPE>
; __device__ __forceinline__ void scan_task(const Args& a, int task, unsigned char* lds) {
;     ...
;     for (int n = 0; n < NCH; n += 2) {
;         scan_load<TYPE>(R1, a, (size_t)bh * 64 + n + 1, w, mt, fr, fq, e0);
;         scan_step<TYPE>(R0, a, Sacc, St, Vn, w, mt, fr, fq, Obase + (size_t)n * 64 * 640);
;         scan_load<TYPE>(R0, a, (size_t)bh * 64 + (n + 2 < NCH ? n + 2 : NCH - 1), w, mt, fr, fq, e0);
;         scan_step<TYPE>(R1, a, Sacc, St, Vn, w, mt, fr, fq, Obase + (size_t)(n + 1) * 64 * 640);
;     }
; }
.LBB0_581:
	s_setprio 0
	s_mov_b64 s[2:3], 0
